# P4 delta-rule chunk solve on the f32 matrix cores (v_mfma_f32_16x16x4_f32, blocked forward substitution with 16x16 diagonal inverses), all eight waves
# speedup vs baseline: 1.0177x; 1.0177x over previous
.LBB0_763:
	v_mov_b32_e32 v32, 0x17c00
	s_waitcnt lgkmcnt(0)
	v_mov_b32_e32 v33, 0x24400
	s_barrier
	s_mov_b64 exec, -1
	v_and_b32_e32 v201, 15, v206
	v_lshrrev_b32_e32 v212, 6, v206
	v_and_b32_e32 v210, 63, v206
	v_lshrrev_b32_e32 v210, 4, v210
	v_readfirstlane_b32 s91, v212
	s_nop 7
	s_nop 7
	s_and_b32 s92, s91, 3
	s_lshl_b32 s92, s92, 6
	v_lshlrev_b32_e32 v211, 1, v201
	v_lshrrev_b32_e32 v212, 6, v206
	v_and_b32_e32 v212, 3, v212
	v_lshl_add_u32 v211, v212, 6, v211
	v_lshlrev_b32_e32 v190, 4, v210
	v_add_u32_e32 v190, 0x24400, v190
	ds_read_b128 v[90:93], v190 offset:512
	ds_read_b128 v[94:97], v190 offset:576
	ds_read_b128 v[98:101], v190 offset:640
	ds_read_b128 v[246:249], v190 offset:704
	s_cmp_ge_u32 s91, 4
	s_cbranch_scc1 .Ldm_kinit
	v_lshl_add_u32 v255, v210, 10, v211
	v_add_u32_e32 v255, 0x1fc00, v255
	v_lshl_add_u32 v245, v210, 10, v211
	v_add_u32_e32 v245, 0x1bc00, v245
	ds_read_u16 v213, v255
	ds_read_u16 v214, v255 offset:256
	ds_read_u16 v215, v255 offset:512
	ds_read_u16 v216, v255 offset:768
	ds_read_u16 v217, v255 offset:32
	ds_read_u16 v218, v255 offset:288
	ds_read_u16 v219, v255 offset:544
	ds_read_u16 v220, v255 offset:800
	s_waitcnt lgkmcnt(0)
	ds_read_u16 v221, v255 offset:4096
	ds_read_u16 v222, v255 offset:4352
	ds_read_u16 v223, v255 offset:4608
	ds_read_u16 v224, v255 offset:4864
	ds_read_u16 v225, v255 offset:4128
	ds_read_u16 v226, v255 offset:4384
	ds_read_u16 v227, v255 offset:4640
	ds_read_u16 v228, v255 offset:4896
	v_lshlrev_b32_e32 v213, 16, v213
	v_lshlrev_b32_e32 v214, 16, v214
	v_lshlrev_b32_e32 v215, 16, v215
	v_lshlrev_b32_e32 v216, 16, v216
	v_lshlrev_b32_e32 v217, 16, v217
	v_lshlrev_b32_e32 v218, 16, v218
	v_lshlrev_b32_e32 v219, 16, v219
	v_lshlrev_b32_e32 v220, 16, v220
	v_mul_f32_e32 v104, v90, v213
	v_sub_f32_e32 v104, 0, v104
	v_mul_f32_e32 v105, v91, v214
	v_sub_f32_e32 v105, 0, v105
	v_mul_f32_e32 v106, v92, v215
	v_sub_f32_e32 v106, 0, v106
	v_mul_f32_e32 v107, v93, v216
	v_sub_f32_e32 v107, 0, v107
	v_mul_f32_e32 v108, v90, v217
	v_sub_f32_e32 v108, 0, v108
	v_mul_f32_e32 v109, v91, v218
	v_sub_f32_e32 v109, 0, v109
	v_mul_f32_e32 v110, v92, v219
	v_sub_f32_e32 v110, 0, v110
	v_mul_f32_e32 v111, v93, v220
	v_sub_f32_e32 v111, 0, v111
	s_waitcnt lgkmcnt(0)
	ds_read_u16 v229, v255 offset:8192
	ds_read_u16 v230, v255 offset:8448
	ds_read_u16 v231, v255 offset:8704
	ds_read_u16 v232, v255 offset:8960
	ds_read_u16 v233, v255 offset:8224
	ds_read_u16 v234, v255 offset:8480
	ds_read_u16 v235, v255 offset:8736
	ds_read_u16 v236, v255 offset:8992
	v_lshlrev_b32_e32 v221, 16, v221
	v_lshlrev_b32_e32 v222, 16, v222
	v_lshlrev_b32_e32 v223, 16, v223
	v_lshlrev_b32_e32 v224, 16, v224
	v_lshlrev_b32_e32 v225, 16, v225
	v_lshlrev_b32_e32 v226, 16, v226
	v_lshlrev_b32_e32 v227, 16, v227
	v_lshlrev_b32_e32 v228, 16, v228
	v_mul_f32_e32 v112, v94, v221
	v_sub_f32_e32 v112, 0, v112
	v_mul_f32_e32 v113, v95, v222
	v_sub_f32_e32 v113, 0, v113
	v_mul_f32_e32 v114, v96, v223
	v_sub_f32_e32 v114, 0, v114
	v_mul_f32_e32 v115, v97, v224
	v_sub_f32_e32 v115, 0, v115
	v_mul_f32_e32 v116, v94, v225
	v_sub_f32_e32 v116, 0, v116
	v_mul_f32_e32 v117, v95, v226
	v_sub_f32_e32 v117, 0, v117
	v_mul_f32_e32 v118, v96, v227
	v_sub_f32_e32 v118, 0, v118
	v_mul_f32_e32 v119, v97, v228
	v_sub_f32_e32 v119, 0, v119
	s_waitcnt lgkmcnt(0)
	ds_read_u16 v237, v255 offset:12288
	ds_read_u16 v238, v255 offset:12544
	ds_read_u16 v239, v255 offset:12800
	ds_read_u16 v240, v255 offset:13056
	ds_read_u16 v241, v255 offset:12320
	ds_read_u16 v242, v255 offset:12576
	ds_read_u16 v243, v255 offset:12832
	ds_read_u16 v244, v255 offset:13088
	v_lshlrev_b32_e32 v229, 16, v229
	v_lshlrev_b32_e32 v230, 16, v230
	v_lshlrev_b32_e32 v231, 16, v231
	v_lshlrev_b32_e32 v232, 16, v232
	v_lshlrev_b32_e32 v233, 16, v233
	v_lshlrev_b32_e32 v234, 16, v234
	v_lshlrev_b32_e32 v235, 16, v235
	v_lshlrev_b32_e32 v236, 16, v236
	v_mul_f32_e32 v120, v98, v229
	v_sub_f32_e32 v120, 0, v120
	v_mul_f32_e32 v121, v99, v230
	v_sub_f32_e32 v121, 0, v121
	v_mul_f32_e32 v122, v100, v231
	v_sub_f32_e32 v122, 0, v122
	v_mul_f32_e32 v123, v101, v232
	v_sub_f32_e32 v123, 0, v123
	v_mul_f32_e32 v124, v98, v233
	v_sub_f32_e32 v124, 0, v124
	v_mul_f32_e32 v125, v99, v234
	v_sub_f32_e32 v125, 0, v125
	v_mul_f32_e32 v126, v100, v235
	v_sub_f32_e32 v126, 0, v126
	v_mul_f32_e32 v127, v101, v236
	v_sub_f32_e32 v127, 0, v127
	s_waitcnt lgkmcnt(0)
	v_lshlrev_b32_e32 v237, 16, v237
	v_lshlrev_b32_e32 v238, 16, v238
	v_lshlrev_b32_e32 v239, 16, v239
	v_lshlrev_b32_e32 v240, 16, v240
	v_lshlrev_b32_e32 v241, 16, v241
	v_lshlrev_b32_e32 v242, 16, v242
	v_lshlrev_b32_e32 v243, 16, v243
	v_lshlrev_b32_e32 v244, 16, v244
	v_mul_f32_e32 v128, v246, v237
	v_sub_f32_e32 v128, 0, v128
	v_mul_f32_e32 v129, v247, v238
	v_sub_f32_e32 v129, 0, v129
	v_mul_f32_e32 v130, v248, v239
	v_sub_f32_e32 v130, 0, v130
	v_mul_f32_e32 v131, v249, v240
	v_sub_f32_e32 v131, 0, v131
	v_mul_f32_e32 v132, v246, v241
	v_sub_f32_e32 v132, 0, v132
	v_mul_f32_e32 v133, v247, v242
	v_sub_f32_e32 v133, 0, v133
	v_mul_f32_e32 v134, v248, v243
	v_sub_f32_e32 v134, 0, v134
	v_mul_f32_e32 v135, v249, v244
	v_sub_f32_e32 v135, 0, v135
	s_branch .Ldm_inited
.Ldm_kinit:
	v_mov_b32_e32 v212, 0x440
	v_mul_u32_u24_e32 v255, v210, v212
	v_add_u32_e32 v255, v211, v255
	v_add_u32_e32 v245, 0x1fc00, v255
	v_add_u32_e32 v255, 0x4400, v255
	ds_read_b128 v[250:253], v190 offset:256
	ds_read_b128 v[202:205], v190 offset:320
	ds_read_b128 v[32:35], v190 offset:384
	ds_read_b128 v[168:171], v190 offset:448
	s_waitcnt lgkmcnt(0)
	ds_read_u16 v213, v255
	ds_read_u16 v214, v255 offset:272
	ds_read_u16 v215, v255 offset:544
	ds_read_u16 v216, v255 offset:816
	ds_read_u16 v217, v255 offset:32
	ds_read_u16 v218, v255 offset:304
	ds_read_u16 v219, v255 offset:576
	ds_read_u16 v220, v255 offset:848
	v_mul_f32_e32 v90, v90, v250
	v_mul_f32_e32 v91, v91, v251
	v_mul_f32_e32 v92, v92, v252
	v_mul_f32_e32 v93, v93, v253
	v_mul_f32_e32 v94, v94, v202
	v_mul_f32_e32 v95, v95, v203
	v_mul_f32_e32 v96, v96, v204
	v_mul_f32_e32 v97, v97, v205
	v_mul_f32_e32 v98, v98, v32
	v_mul_f32_e32 v99, v99, v33
	v_mul_f32_e32 v100, v100, v34
	v_mul_f32_e32 v101, v101, v35
	v_mul_f32_e32 v246, v246, v168
	v_mul_f32_e32 v247, v247, v169
	v_mul_f32_e32 v248, v248, v170
	v_mul_f32_e32 v249, v249, v171
	s_waitcnt lgkmcnt(0)
	ds_read_u16 v221, v255 offset:4352
	ds_read_u16 v222, v255 offset:4624
	ds_read_u16 v223, v255 offset:4896
	ds_read_u16 v224, v255 offset:5168
	ds_read_u16 v225, v255 offset:4384
	ds_read_u16 v226, v255 offset:4656
	ds_read_u16 v227, v255 offset:4928
	ds_read_u16 v228, v255 offset:5200
	v_lshlrev_b32_e32 v213, 16, v213
	v_lshlrev_b32_e32 v214, 16, v214
	v_lshlrev_b32_e32 v215, 16, v215
	v_lshlrev_b32_e32 v216, 16, v216
	v_lshlrev_b32_e32 v217, 16, v217
	v_lshlrev_b32_e32 v218, 16, v218
	v_lshlrev_b32_e32 v219, 16, v219
	v_lshlrev_b32_e32 v220, 16, v220
	v_mul_f32_e32 v104, v90, v213
	v_sub_f32_e32 v104, 0, v104
	v_mul_f32_e32 v105, v91, v214
	v_sub_f32_e32 v105, 0, v105
	v_mul_f32_e32 v106, v92, v215
	v_sub_f32_e32 v106, 0, v106
	v_mul_f32_e32 v107, v93, v216
	v_sub_f32_e32 v107, 0, v107
	v_mul_f32_e32 v108, v90, v217
	v_sub_f32_e32 v108, 0, v108
	v_mul_f32_e32 v109, v91, v218
	v_sub_f32_e32 v109, 0, v109
	v_mul_f32_e32 v110, v92, v219
	v_sub_f32_e32 v110, 0, v110
	v_mul_f32_e32 v111, v93, v220
	v_sub_f32_e32 v111, 0, v111
	s_waitcnt lgkmcnt(0)
	ds_read_u16 v229, v255 offset:8704
	ds_read_u16 v230, v255 offset:8976
	ds_read_u16 v231, v255 offset:9248
	ds_read_u16 v232, v255 offset:9520
	ds_read_u16 v233, v255 offset:8736
	ds_read_u16 v234, v255 offset:9008
	ds_read_u16 v235, v255 offset:9280
	ds_read_u16 v236, v255 offset:9552
	v_lshlrev_b32_e32 v221, 16, v221
	v_lshlrev_b32_e32 v222, 16, v222
	v_lshlrev_b32_e32 v223, 16, v223
	v_lshlrev_b32_e32 v224, 16, v224
	v_lshlrev_b32_e32 v225, 16, v225
	v_lshlrev_b32_e32 v226, 16, v226
	v_lshlrev_b32_e32 v227, 16, v227
	v_lshlrev_b32_e32 v228, 16, v228
	v_mul_f32_e32 v112, v94, v221
	v_sub_f32_e32 v112, 0, v112
	v_mul_f32_e32 v113, v95, v222
	v_sub_f32_e32 v113, 0, v113
	v_mul_f32_e32 v114, v96, v223
	v_sub_f32_e32 v114, 0, v114
	v_mul_f32_e32 v115, v97, v224
	v_sub_f32_e32 v115, 0, v115
	v_mul_f32_e32 v116, v94, v225
	v_sub_f32_e32 v116, 0, v116
	v_mul_f32_e32 v117, v95, v226
	v_sub_f32_e32 v117, 0, v117
	v_mul_f32_e32 v118, v96, v227
	v_sub_f32_e32 v118, 0, v118
	v_mul_f32_e32 v119, v97, v228
	v_sub_f32_e32 v119, 0, v119
	s_waitcnt lgkmcnt(0)
	ds_read_u16 v237, v255 offset:13056
	ds_read_u16 v238, v255 offset:13328
	ds_read_u16 v239, v255 offset:13600
	ds_read_u16 v240, v255 offset:13872
	ds_read_u16 v241, v255 offset:13088
	ds_read_u16 v242, v255 offset:13360
	ds_read_u16 v243, v255 offset:13632
	ds_read_u16 v244, v255 offset:13904
	v_lshlrev_b32_e32 v229, 16, v229
	v_lshlrev_b32_e32 v230, 16, v230
	v_lshlrev_b32_e32 v231, 16, v231
	v_lshlrev_b32_e32 v232, 16, v232
	v_lshlrev_b32_e32 v233, 16, v233
	v_lshlrev_b32_e32 v234, 16, v234
	v_lshlrev_b32_e32 v235, 16, v235
	v_lshlrev_b32_e32 v236, 16, v236
	v_mul_f32_e32 v120, v98, v229
	v_sub_f32_e32 v120, 0, v120
	v_mul_f32_e32 v121, v99, v230
	v_sub_f32_e32 v121, 0, v121
	v_mul_f32_e32 v122, v100, v231
	v_sub_f32_e32 v122, 0, v122
	v_mul_f32_e32 v123, v101, v232
	v_sub_f32_e32 v123, 0, v123
	v_mul_f32_e32 v124, v98, v233
	v_sub_f32_e32 v124, 0, v124
	v_mul_f32_e32 v125, v99, v234
	v_sub_f32_e32 v125, 0, v125
	v_mul_f32_e32 v126, v100, v235
	v_sub_f32_e32 v126, 0, v126
	v_mul_f32_e32 v127, v101, v236
	v_sub_f32_e32 v127, 0, v127
	s_waitcnt lgkmcnt(0)
	v_lshlrev_b32_e32 v237, 16, v237
	v_lshlrev_b32_e32 v238, 16, v238
	v_lshlrev_b32_e32 v239, 16, v239
	v_lshlrev_b32_e32 v240, 16, v240
	v_lshlrev_b32_e32 v241, 16, v241
	v_lshlrev_b32_e32 v242, 16, v242
	v_lshlrev_b32_e32 v243, 16, v243
	v_lshlrev_b32_e32 v244, 16, v244
	v_mul_f32_e32 v128, v246, v237
	v_sub_f32_e32 v128, 0, v128
	v_mul_f32_e32 v129, v247, v238
	v_sub_f32_e32 v129, 0, v129
	v_mul_f32_e32 v130, v248, v239
	v_sub_f32_e32 v130, 0, v130
	v_mul_f32_e32 v131, v249, v240
	v_sub_f32_e32 v131, 0, v131
	v_mul_f32_e32 v132, v246, v241
	v_sub_f32_e32 v132, 0, v132
	v_mul_f32_e32 v133, v247, v242
	v_sub_f32_e32 v133, 0, v133
	v_mul_f32_e32 v134, v248, v243
	v_sub_f32_e32 v134, 0, v134
	v_mul_f32_e32 v135, v249, v244
	v_sub_f32_e32 v135, 0, v135
.Ldm_inited:
	v_and_b32_e32 v174, 15, v206
	v_and_b32_e32 v175, 63, v206
	v_lshrrev_b32_e32 v175, 4, v175
	s_cmp_eq_u32 s91, 7
	s_cbranch_scc0 .Ldm_not
	v_lshlrev_b32_e32 v176, 12, v175
	v_lshl_add_u32 v176, v175, 6, v176
	v_add_u32_e32 v176, 0x17c00, v176
	v_lshlrev_b32_e32 v172, 10, v175
	v_lshl_add_u32 v172, v174, 2, v172
	v_add_u32_e32 v172, 0x24800, v172
	v_mov_b32_e32 v173, 0
	v_cmp_eq_u32_e64 vcc, v174, 0
	s_nop 1
	v_cndmask_b32_e64 v36, v173, 1.0, vcc
	v_cmp_eq_u32_e64 vcc, v174, 1
	s_nop 1
	v_cndmask_b32_e64 v37, v173, 1.0, vcc
	v_cmp_eq_u32_e64 vcc, v174, 2
	s_nop 1
	v_cndmask_b32_e64 v38, v173, 1.0, vcc
	v_cmp_eq_u32_e64 vcc, v174, 3
	s_nop 1
	v_cndmask_b32_e64 v39, v173, 1.0, vcc
	v_cmp_eq_u32_e64 vcc, v174, 4
	s_nop 1
	v_cndmask_b32_e64 v40, v173, 1.0, vcc
	v_cmp_eq_u32_e64 vcc, v174, 5
	s_nop 1
	v_cndmask_b32_e64 v41, v173, 1.0, vcc
	v_cmp_eq_u32_e64 vcc, v174, 6
	s_nop 1
	v_cndmask_b32_e64 v42, v173, 1.0, vcc
	v_cmp_eq_u32_e64 vcc, v174, 7
	s_nop 1
	v_cndmask_b32_e64 v43, v173, 1.0, vcc
	v_cmp_eq_u32_e64 vcc, v174, 8
	s_nop 1
	v_cndmask_b32_e64 v44, v173, 1.0, vcc
	v_cmp_eq_u32_e64 vcc, v174, 9
	s_nop 1
	v_cndmask_b32_e64 v45, v173, 1.0, vcc
	v_cmp_eq_u32_e64 vcc, v174, 10
	s_nop 1
	v_cndmask_b32_e64 v46, v173, 1.0, vcc
	v_cmp_eq_u32_e64 vcc, v174, 11
	s_nop 1
	v_cndmask_b32_e64 v47, v173, 1.0, vcc
	v_cmp_eq_u32_e64 vcc, v174, 12
	s_nop 1
	v_cndmask_b32_e64 v32, v173, 1.0, vcc
	v_cmp_eq_u32_e64 vcc, v174, 13
	s_nop 1
	v_cndmask_b32_e64 v33, v173, 1.0, vcc
	v_cmp_eq_u32_e64 vcc, v174, 14
	s_nop 1
	v_cndmask_b32_e64 v34, v173, 1.0, vcc
	v_cmp_eq_u32_e64 vcc, v174, 15
	s_nop 1
	v_cndmask_b32_e64 v35, v173, 1.0, vcc
	ds_read_b128 v[136:139], v176 offset:256
	ds_read_b128 v[140:143], v176 offset:512
	ds_read_b128 v[144:147], v176 offset:768
	ds_read_b128 v[148:151], v176 offset:1024
	ds_read_b128 v[152:155], v176 offset:1280
	ds_read_b128 v[156:159], v176 offset:1296
	s_waitcnt lgkmcnt(0)
	v_fma_f32 v37, -v136, v36, v37
	v_fma_f32 v38, -v140, v36, v38
	v_fma_f32 v38, -v141, v37, v38
	v_fma_f32 v39, -v144, v36, v39
	v_fma_f32 v39, -v145, v37, v39
	v_fma_f32 v39, -v146, v38, v39
	v_fma_f32 v40, -v148, v36, v40
	v_fma_f32 v40, -v149, v37, v40
	v_fma_f32 v40, -v150, v38, v40
	v_fma_f32 v40, -v151, v39, v40
	v_fma_f32 v41, -v152, v36, v41
	v_fma_f32 v41, -v153, v37, v41
	v_fma_f32 v41, -v154, v38, v41
	v_fma_f32 v41, -v155, v39, v41
	v_fma_f32 v41, -v156, v40, v41
	ds_read_b128 v[136:139], v176 offset:1536
	ds_read_b128 v[140:143], v176 offset:1552
	ds_read_b128 v[144:147], v176 offset:1792
	ds_read_b128 v[148:151], v176 offset:1808
	ds_read_b128 v[152:155], v176 offset:2048
	ds_read_b128 v[156:159], v176 offset:2064
	ds_read_b128 v[160:163], v176 offset:2304
	ds_read_b128 v[164:167], v176 offset:2320
	ds_read_b128 v[168:171], v176 offset:2336
	s_waitcnt lgkmcnt(0)
	v_fma_f32 v42, -v136, v36, v42
	v_fma_f32 v42, -v137, v37, v42
	v_fma_f32 v42, -v138, v38, v42
	v_fma_f32 v42, -v139, v39, v42
	v_fma_f32 v42, -v140, v40, v42
	v_fma_f32 v42, -v141, v41, v42
	v_fma_f32 v43, -v144, v36, v43
	v_fma_f32 v43, -v145, v37, v43
	v_fma_f32 v43, -v146, v38, v43
	v_fma_f32 v43, -v147, v39, v43
	v_fma_f32 v43, -v148, v40, v43
	v_fma_f32 v43, -v149, v41, v43
	v_fma_f32 v43, -v150, v42, v43
	v_fma_f32 v44, -v152, v36, v44
	v_fma_f32 v44, -v153, v37, v44
	v_fma_f32 v44, -v154, v38, v44
	v_fma_f32 v44, -v155, v39, v44
	v_fma_f32 v44, -v156, v40, v44
	v_fma_f32 v44, -v157, v41, v44
	v_fma_f32 v44, -v158, v42, v44
	v_fma_f32 v44, -v159, v43, v44
	v_fma_f32 v45, -v160, v36, v45
	v_fma_f32 v45, -v161, v37, v45
	v_fma_f32 v45, -v162, v38, v45
	v_fma_f32 v45, -v163, v39, v45
	v_fma_f32 v45, -v164, v40, v45
	v_fma_f32 v45, -v165, v41, v45
	v_fma_f32 v45, -v166, v42, v45
	v_fma_f32 v45, -v167, v43, v45
	v_fma_f32 v45, -v168, v44, v45
	ds_read_b128 v[136:139], v176 offset:2560
	ds_read_b128 v[140:143], v176 offset:2576
	ds_read_b128 v[144:147], v176 offset:2592
	ds_read_b128 v[148:151], v176 offset:2816
	ds_read_b128 v[152:155], v176 offset:2832
	ds_read_b128 v[156:159], v176 offset:2848
	ds_read_b128 v[160:163], v176 offset:3072
	ds_read_b128 v[164:167], v176 offset:3088
	ds_read_b128 v[168:171], v176 offset:3104
	s_waitcnt lgkmcnt(0)
	v_fma_f32 v46, -v136, v36, v46
	v_fma_f32 v46, -v137, v37, v46
	v_fma_f32 v46, -v138, v38, v46
	v_fma_f32 v46, -v139, v39, v46
	v_fma_f32 v46, -v140, v40, v46
	v_fma_f32 v46, -v141, v41, v46
	v_fma_f32 v46, -v142, v42, v46
	v_fma_f32 v46, -v143, v43, v46
	v_fma_f32 v46, -v144, v44, v46
	v_fma_f32 v46, -v145, v45, v46
	v_fma_f32 v47, -v148, v36, v47
	v_fma_f32 v47, -v149, v37, v47
	v_fma_f32 v47, -v150, v38, v47
	v_fma_f32 v47, -v151, v39, v47
	v_fma_f32 v47, -v152, v40, v47
	v_fma_f32 v47, -v153, v41, v47
	v_fma_f32 v47, -v154, v42, v47
	v_fma_f32 v47, -v155, v43, v47
	v_fma_f32 v47, -v156, v44, v47
	v_fma_f32 v47, -v157, v45, v47
	v_fma_f32 v47, -v158, v46, v47
	v_fma_f32 v32, -v160, v36, v32
	v_fma_f32 v32, -v161, v37, v32
	v_fma_f32 v32, -v162, v38, v32
	v_fma_f32 v32, -v163, v39, v32
	v_fma_f32 v32, -v164, v40, v32
	v_fma_f32 v32, -v165, v41, v32
	v_fma_f32 v32, -v166, v42, v32
	v_fma_f32 v32, -v167, v43, v32
	v_fma_f32 v32, -v168, v44, v32
	v_fma_f32 v32, -v169, v45, v32
	v_fma_f32 v32, -v170, v46, v32
	v_fma_f32 v32, -v171, v47, v32
	ds_read_b128 v[136:139], v176 offset:3328
	ds_read_b128 v[140:143], v176 offset:3344
	ds_read_b128 v[144:147], v176 offset:3360
	ds_read_b128 v[148:151], v176 offset:3376
	ds_read_b128 v[152:155], v176 offset:3584
	ds_read_b128 v[156:159], v176 offset:3600
	ds_read_b128 v[160:163], v176 offset:3616
	ds_read_b128 v[164:167], v176 offset:3632
	s_waitcnt lgkmcnt(0)
	v_fma_f32 v33, -v136, v36, v33
	v_fma_f32 v33, -v137, v37, v33
	v_fma_f32 v33, -v138, v38, v33
	v_fma_f32 v33, -v139, v39, v33
	v_fma_f32 v33, -v140, v40, v33
	v_fma_f32 v33, -v141, v41, v33
	v_fma_f32 v33, -v142, v42, v33
	v_fma_f32 v33, -v143, v43, v33
	v_fma_f32 v33, -v144, v44, v33
	v_fma_f32 v33, -v145, v45, v33
	v_fma_f32 v33, -v146, v46, v33
	v_fma_f32 v33, -v147, v47, v33
	v_fma_f32 v33, -v148, v32, v33
	v_fma_f32 v34, -v152, v36, v34
	v_fma_f32 v34, -v153, v37, v34
	v_fma_f32 v34, -v154, v38, v34
	v_fma_f32 v34, -v155, v39, v34
	v_fma_f32 v34, -v156, v40, v34
	v_fma_f32 v34, -v157, v41, v34
	v_fma_f32 v34, -v158, v42, v34
	v_fma_f32 v34, -v159, v43, v34
	v_fma_f32 v34, -v160, v44, v34
	v_fma_f32 v34, -v161, v45, v34
	v_fma_f32 v34, -v162, v46, v34
	v_fma_f32 v34, -v163, v47, v34
	v_fma_f32 v34, -v164, v32, v34
	v_fma_f32 v34, -v165, v33, v34
	ds_read_b128 v[136:139], v176 offset:3840
	ds_read_b128 v[140:143], v176 offset:3856
	ds_read_b128 v[144:147], v176 offset:3872
	ds_read_b128 v[148:151], v176 offset:3888
	s_waitcnt lgkmcnt(0)
	v_fma_f32 v35, -v136, v36, v35
	v_fma_f32 v35, -v137, v37, v35
	v_fma_f32 v35, -v138, v38, v35
	v_fma_f32 v35, -v139, v39, v35
	v_fma_f32 v35, -v140, v40, v35
	v_fma_f32 v35, -v141, v41, v35
	v_fma_f32 v35, -v142, v42, v35
	v_fma_f32 v35, -v143, v43, v35
	v_fma_f32 v35, -v144, v44, v35
	v_fma_f32 v35, -v145, v45, v35
	v_fma_f32 v35, -v146, v46, v35
	v_fma_f32 v35, -v147, v47, v35
	v_fma_f32 v35, -v148, v32, v35
	v_fma_f32 v35, -v149, v33, v35
	v_fma_f32 v35, -v150, v34, v35
	v_sub_f32_e32 v36, 0, v36
	ds_write_b32 v172, v36
	v_sub_f32_e32 v37, 0, v37
	ds_write_b32 v172, v37 offset:64
	v_sub_f32_e32 v38, 0, v38
	ds_write_b32 v172, v38 offset:128
	v_sub_f32_e32 v39, 0, v39
	ds_write_b32 v172, v39 offset:192
	v_sub_f32_e32 v40, 0, v40
	ds_write_b32 v172, v40 offset:256
	v_sub_f32_e32 v41, 0, v41
	ds_write_b32 v172, v41 offset:320
	v_sub_f32_e32 v42, 0, v42
	ds_write_b32 v172, v42 offset:384
	v_sub_f32_e32 v43, 0, v43
	ds_write_b32 v172, v43 offset:448
	s_waitcnt lgkmcnt(0)
	v_sub_f32_e32 v44, 0, v44
	ds_write_b32 v172, v44 offset:512
	v_sub_f32_e32 v45, 0, v45
	ds_write_b32 v172, v45 offset:576
	v_sub_f32_e32 v46, 0, v46
	ds_write_b32 v172, v46 offset:640
	v_sub_f32_e32 v47, 0, v47
	ds_write_b32 v172, v47 offset:704
	v_sub_f32_e32 v32, 0, v32
	ds_write_b32 v172, v32 offset:768
	v_sub_f32_e32 v33, 0, v33
	ds_write_b32 v172, v33 offset:832
	v_sub_f32_e32 v34, 0, v34
	ds_write_b32 v172, v34 offset:896
	v_sub_f32_e32 v35, 0, v35
	ds_write_b32 v172, v35 offset:960
.Ldm_not:
	s_waitcnt lgkmcnt(0)
	s_barrier
	v_lshlrev_b32_e32 v211, 8, v201
	v_lshl_add_u32 v211, v210, 4, v211
	v_add_u32_e32 v211, 0x17c00, v211
	v_lshlrev_b32_e32 v212, 6, v201
	v_lshl_add_u32 v212, v210, 4, v212
	v_add_u32_e32 v212, 0x24800, v212
	ds_read_b128 v[36:39], v212
	ds_read_b128 v[40:43], v212 offset:1024
	ds_read_b128 v[44:47], v212 offset:2048
	ds_read_b128 v[86:89], v212 offset:3072
	ds_read_b128 v[168:171], v211 offset:4096
	ds_read_b128 v[172:175], v211 offset:8192
	ds_read_b128 v[176:179], v211 offset:8256
	ds_read_b128 v[180:183], v211 offset:12288
	ds_read_b128 v[184:187], v211 offset:12352
	ds_read_b128 v[32:35], v211 offset:12416
	v_mov_b32_e32 v136, 0
	v_mov_b32_e32 v137, 0
	v_mov_b32_e32 v138, 0
	v_mov_b32_e32 v139, 0
	v_mov_b32_e32 v140, 0
	v_mov_b32_e32 v141, 0
	v_mov_b32_e32 v142, 0
	v_mov_b32_e32 v143, 0
	v_mov_b32_e32 v144, 0
	v_mov_b32_e32 v145, 0
	v_mov_b32_e32 v146, 0
	v_mov_b32_e32 v147, 0
	v_mov_b32_e32 v148, 0
	v_mov_b32_e32 v149, 0
	v_mov_b32_e32 v150, 0
	v_mov_b32_e32 v151, 0
	v_mov_b32_e32 v152, 0
	v_mov_b32_e32 v153, 0
	v_mov_b32_e32 v154, 0
	v_mov_b32_e32 v155, 0
	v_mov_b32_e32 v156, 0
	v_mov_b32_e32 v157, 0
	v_mov_b32_e32 v158, 0
	v_mov_b32_e32 v159, 0
	v_mov_b32_e32 v160, 0
	v_mov_b32_e32 v161, 0
	v_mov_b32_e32 v162, 0
	v_mov_b32_e32 v163, 0
	v_mov_b32_e32 v164, 0
	v_mov_b32_e32 v165, 0
	v_mov_b32_e32 v166, 0
	v_mov_b32_e32 v167, 0
	s_waitcnt lgkmcnt(0)
	v_mfma_f32_16x16x4_f32 v[136:139], v36, v104, v[136:139]
	v_mfma_f32_16x16x4_f32 v[140:143], v36, v108, v[140:143]
	v_mfma_f32_16x16x4_f32 v[136:139], v37, v105, v[136:139]
	v_mfma_f32_16x16x4_f32 v[140:143], v37, v109, v[140:143]
	v_mfma_f32_16x16x4_f32 v[136:139], v38, v106, v[136:139]
	v_mfma_f32_16x16x4_f32 v[140:143], v38, v110, v[140:143]
	v_mfma_f32_16x16x4_f32 v[136:139], v39, v107, v[136:139]
	v_mfma_f32_16x16x4_f32 v[140:143], v39, v111, v[140:143]
	s_nop 7
	s_nop 7
	s_nop 7
	v_mfma_f32_16x16x4_f32 v[112:115], v168, v136, v[112:115]
	v_mfma_f32_16x16x4_f32 v[116:119], v168, v140, v[116:119]
	v_mfma_f32_16x16x4_f32 v[112:115], v169, v137, v[112:115]
	v_mfma_f32_16x16x4_f32 v[116:119], v169, v141, v[116:119]
	v_mfma_f32_16x16x4_f32 v[112:115], v170, v138, v[112:115]
	v_mfma_f32_16x16x4_f32 v[116:119], v170, v142, v[116:119]
	v_mfma_f32_16x16x4_f32 v[112:115], v171, v139, v[112:115]
	v_mfma_f32_16x16x4_f32 v[116:119], v171, v143, v[116:119]
	s_nop 7
	s_nop 7
	s_nop 7
	v_mfma_f32_16x16x4_f32 v[144:147], v40, v112, v[144:147]
	v_mfma_f32_16x16x4_f32 v[148:151], v40, v116, v[148:151]
	v_mfma_f32_16x16x4_f32 v[144:147], v41, v113, v[144:147]
	v_mfma_f32_16x16x4_f32 v[148:151], v41, v117, v[148:151]
	v_mfma_f32_16x16x4_f32 v[144:147], v42, v114, v[144:147]
	v_mfma_f32_16x16x4_f32 v[148:151], v42, v118, v[148:151]
	v_mfma_f32_16x16x4_f32 v[144:147], v43, v115, v[144:147]
	v_mfma_f32_16x16x4_f32 v[148:151], v43, v119, v[148:151]
	s_nop 7
	s_nop 7
	s_nop 7
	v_mfma_f32_16x16x4_f32 v[120:123], v172, v136, v[120:123]
	v_mfma_f32_16x16x4_f32 v[124:127], v172, v140, v[124:127]
	v_mfma_f32_16x16x4_f32 v[120:123], v173, v137, v[120:123]
	v_mfma_f32_16x16x4_f32 v[124:127], v173, v141, v[124:127]
	v_mfma_f32_16x16x4_f32 v[120:123], v174, v138, v[120:123]
	v_mfma_f32_16x16x4_f32 v[124:127], v174, v142, v[124:127]
	v_mfma_f32_16x16x4_f32 v[120:123], v175, v139, v[120:123]
	v_mfma_f32_16x16x4_f32 v[124:127], v175, v143, v[124:127]
	v_mfma_f32_16x16x4_f32 v[120:123], v176, v144, v[120:123]
	v_mfma_f32_16x16x4_f32 v[124:127], v176, v148, v[124:127]
	v_mfma_f32_16x16x4_f32 v[120:123], v177, v145, v[120:123]
	v_mfma_f32_16x16x4_f32 v[124:127], v177, v149, v[124:127]
	v_mfma_f32_16x16x4_f32 v[120:123], v178, v146, v[120:123]
	v_mfma_f32_16x16x4_f32 v[124:127], v178, v150, v[124:127]
	v_mfma_f32_16x16x4_f32 v[120:123], v179, v147, v[120:123]
	v_mfma_f32_16x16x4_f32 v[124:127], v179, v151, v[124:127]
	s_nop 7
	s_nop 7
	s_nop 7
	v_mfma_f32_16x16x4_f32 v[152:155], v44, v120, v[152:155]
	v_mfma_f32_16x16x4_f32 v[156:159], v44, v124, v[156:159]
	v_mfma_f32_16x16x4_f32 v[152:155], v45, v121, v[152:155]
	v_mfma_f32_16x16x4_f32 v[156:159], v45, v125, v[156:159]
	v_mfma_f32_16x16x4_f32 v[152:155], v46, v122, v[152:155]
	v_mfma_f32_16x16x4_f32 v[156:159], v46, v126, v[156:159]
	v_mfma_f32_16x16x4_f32 v[152:155], v47, v123, v[152:155]
	v_mfma_f32_16x16x4_f32 v[156:159], v47, v127, v[156:159]
	s_nop 7
	s_nop 7
	s_nop 7
	v_mfma_f32_16x16x4_f32 v[128:131], v180, v136, v[128:131]
	v_mfma_f32_16x16x4_f32 v[132:135], v180, v140, v[132:135]
	v_mfma_f32_16x16x4_f32 v[128:131], v181, v137, v[128:131]
	v_mfma_f32_16x16x4_f32 v[132:135], v181, v141, v[132:135]
	v_mfma_f32_16x16x4_f32 v[128:131], v182, v138, v[128:131]
	v_mfma_f32_16x16x4_f32 v[132:135], v182, v142, v[132:135]
	v_mfma_f32_16x16x4_f32 v[128:131], v183, v139, v[128:131]
	v_mfma_f32_16x16x4_f32 v[132:135], v183, v143, v[132:135]
	v_mfma_f32_16x16x4_f32 v[128:131], v184, v144, v[128:131]
	v_mfma_f32_16x16x4_f32 v[132:135], v184, v148, v[132:135]
	v_mfma_f32_16x16x4_f32 v[128:131], v185, v145, v[128:131]
	v_mfma_f32_16x16x4_f32 v[132:135], v185, v149, v[132:135]
	v_mfma_f32_16x16x4_f32 v[128:131], v186, v146, v[128:131]
	v_mfma_f32_16x16x4_f32 v[132:135], v186, v150, v[132:135]
	v_mfma_f32_16x16x4_f32 v[128:131], v187, v147, v[128:131]
	v_mfma_f32_16x16x4_f32 v[132:135], v187, v151, v[132:135]
	v_mfma_f32_16x16x4_f32 v[128:131], v32, v152, v[128:131]
	v_mfma_f32_16x16x4_f32 v[132:135], v32, v156, v[132:135]
	v_mfma_f32_16x16x4_f32 v[128:131], v33, v153, v[128:131]
	v_mfma_f32_16x16x4_f32 v[132:135], v33, v157, v[132:135]
	v_mfma_f32_16x16x4_f32 v[128:131], v34, v154, v[128:131]
	v_mfma_f32_16x16x4_f32 v[132:135], v34, v158, v[132:135]
	v_mfma_f32_16x16x4_f32 v[128:131], v35, v155, v[128:131]
	v_mfma_f32_16x16x4_f32 v[132:135], v35, v159, v[132:135]
	s_nop 7
	s_nop 7
	s_nop 7
	v_mfma_f32_16x16x4_f32 v[160:163], v86, v128, v[160:163]
	v_mfma_f32_16x16x4_f32 v[164:167], v86, v132, v[164:167]
	v_mfma_f32_16x16x4_f32 v[160:163], v87, v129, v[160:163]
	v_mfma_f32_16x16x4_f32 v[164:167], v87, v133, v[164:167]
	v_mfma_f32_16x16x4_f32 v[160:163], v88, v130, v[160:163]
	v_mfma_f32_16x16x4_f32 v[164:167], v88, v134, v[164:167]
	v_mfma_f32_16x16x4_f32 v[160:163], v89, v131, v[160:163]
	v_mfma_f32_16x16x4_f32 v[164:167], v89, v135, v[164:167]
	s_nop 7
	s_nop 7
	s_nop 7
	s_cmp_ge_u32 s91, 4
	v_cvt_pk_bf16_f32 v213, v136, 0
	v_cvt_pk_bf16_f32 v214, v137, 0
	v_cvt_pk_bf16_f32 v215, v138, 0
	v_cvt_pk_bf16_f32 v216, v139, 0
	v_cvt_pk_bf16_f32 v217, v140, 0
	v_cvt_pk_bf16_f32 v218, v141, 0
	v_cvt_pk_bf16_f32 v219, v142, 0
	v_cvt_pk_bf16_f32 v220, v143, 0
	v_cvt_pk_bf16_f32 v221, v144, 0
	v_cvt_pk_bf16_f32 v222, v145, 0
	v_cvt_pk_bf16_f32 v223, v146, 0
	v_cvt_pk_bf16_f32 v224, v147, 0
	v_cvt_pk_bf16_f32 v225, v148, 0
	v_cvt_pk_bf16_f32 v226, v149, 0
	v_cvt_pk_bf16_f32 v227, v150, 0
	v_cvt_pk_bf16_f32 v228, v151, 0
	v_cvt_pk_bf16_f32 v229, v152, 0
	v_cvt_pk_bf16_f32 v230, v153, 0
	v_cvt_pk_bf16_f32 v231, v154, 0
	v_cvt_pk_bf16_f32 v232, v155, 0
	v_cvt_pk_bf16_f32 v233, v156, 0
	v_cvt_pk_bf16_f32 v234, v157, 0
	v_cvt_pk_bf16_f32 v235, v158, 0
	v_cvt_pk_bf16_f32 v236, v159, 0
	v_cvt_pk_bf16_f32 v237, v160, 0
	v_cvt_pk_bf16_f32 v238, v161, 0
	v_cvt_pk_bf16_f32 v239, v162, 0
	v_cvt_pk_bf16_f32 v240, v163, 0
	v_cvt_pk_bf16_f32 v241, v164, 0
	v_cvt_pk_bf16_f32 v242, v165, 0
	v_cvt_pk_bf16_f32 v243, v166, 0
	v_cvt_pk_bf16_f32 v244, v167, 0
	s_cbranch_scc1 .Ldm_kout
	ds_write_b16 v245, v213
	ds_write_b16 v245, v214 offset:256
	ds_write_b16 v245, v215 offset:512
	ds_write_b16 v245, v216 offset:768
	ds_write_b16 v245, v217 offset:32
	ds_write_b16 v245, v218 offset:288
	ds_write_b16 v245, v219 offset:544
	ds_write_b16 v245, v220 offset:800
	s_waitcnt lgkmcnt(7)
	ds_write_b16 v245, v221 offset:4096
	ds_write_b16 v245, v222 offset:4352
	ds_write_b16 v245, v223 offset:4608
	ds_write_b16 v245, v224 offset:4864
	ds_write_b16 v245, v225 offset:4128
	ds_write_b16 v245, v226 offset:4384
	ds_write_b16 v245, v227 offset:4640
	ds_write_b16 v245, v228 offset:4896
	s_waitcnt lgkmcnt(7)
	ds_write_b16 v245, v229 offset:8192
	ds_write_b16 v245, v230 offset:8448
	ds_write_b16 v245, v231 offset:8704
	ds_write_b16 v245, v232 offset:8960
	ds_write_b16 v245, v233 offset:8224
	ds_write_b16 v245, v234 offset:8480
	ds_write_b16 v245, v235 offset:8736
	ds_write_b16 v245, v236 offset:8992
	s_waitcnt lgkmcnt(7)
	ds_write_b16 v245, v237 offset:12288
	ds_write_b16 v245, v238 offset:12544
	ds_write_b16 v245, v239 offset:12800
	ds_write_b16 v245, v240 offset:13056
	ds_write_b16 v245, v241 offset:12320
	ds_write_b16 v245, v242 offset:12576
	ds_write_b16 v245, v243 offset:12832
	ds_write_b16 v245, v244 offset:13088
	s_waitcnt lgkmcnt(7)
	s_branch .Ldm_done
.Ldm_kout:
	ds_write_b16 v245, v213
	ds_write_b16 v245, v214 offset:272
	ds_write_b16 v245, v215 offset:544
	ds_write_b16 v245, v216 offset:816
	ds_write_b16 v245, v217 offset:32
	ds_write_b16 v245, v218 offset:304
	ds_write_b16 v245, v219 offset:576
	ds_write_b16 v245, v220 offset:848
	s_waitcnt lgkmcnt(7)
	ds_write_b16 v245, v221 offset:4352
	ds_write_b16 v245, v222 offset:4624
	ds_write_b16 v245, v223 offset:4896
	ds_write_b16 v245, v224 offset:5168
	ds_write_b16 v245, v225 offset:4384
	ds_write_b16 v245, v226 offset:4656
	ds_write_b16 v245, v227 offset:4928
	ds_write_b16 v245, v228 offset:5200
	s_waitcnt lgkmcnt(7)
	ds_write_b16 v245, v229 offset:8704
	ds_write_b16 v245, v230 offset:8976
	ds_write_b16 v245, v231 offset:9248
	ds_write_b16 v245, v232 offset:9520
	ds_write_b16 v245, v233 offset:8736
	ds_write_b16 v245, v234 offset:9008
	ds_write_b16 v245, v235 offset:9280
	ds_write_b16 v245, v236 offset:9552
	s_waitcnt lgkmcnt(7)
	ds_write_b16 v245, v237 offset:13056
	ds_write_b16 v245, v238 offset:13328
	ds_write_b16 v245, v239 offset:13600
	ds_write_b16 v245, v240 offset:13872
	ds_write_b16 v245, v241 offset:13088
	ds_write_b16 v245, v242 offset:13360
	ds_write_b16 v245, v243 offset:13632
	ds_write_b16 v245, v244 offset:13904
	s_waitcnt lgkmcnt(7)
.Ldm_done:
	s_branch .LBB0_602
.LBB0_774:
	v_cndmask_b32_e64 v43, 0, 1, s[66:67]
	v_cmp_ne_u32_e64 s[10:11], 1, v43
	s_andn2_b64 vcc, exec, s[66:67]
	s_cbranch_vccnz .LBB0_611
